# speedup vs baseline: 1.0025x; 1.0025x over previous
; #define LAS __attribute__((address_space(3)))
; #define GAS __attribute__((address_space(1)))
; __device__ __forceinline__ void attn_unit(LAS unsigned char* lds, bf16_t* Qm, const bf16_t* __restrict__ Kb, const bf16_t* __restrict__ Vt,
;                                           int b, int h, int qb, int lgS, float lam, float oscale, const float* __restrict__ subg, float* stash) {
;     ...
;         {
; #pragma unroll
;             for (int blk = 0; blk < 4; ++blk) o[blk] = __builtin_amdgcn_mfma_f32_32x32x16_bf16(vfa[blk], __builtin_bit_cast(bf16x8, pk[0]), o[blk], 0, 0, 0);
; #pragma unroll
;             for (int ks = 1; ks < 4; ++ks)
; #pragma unroll
;                 for (int blk = 0; blk < 4; ++blk) {
;                     const bf16x8 vf = *(const LAS bf16x8*)(lds + vs0 + vr + blk * 32 * VP + ks * 32);
;                     o[blk] = __builtin_amdgcn_mfma_f32_32x32x16_bf16(vf, __builtin_bit_cast(bf16x8, pk[ks]), o[blk], 0, 0, 0);
;                 }
;         }
;         __syncthreads();
;         lrun += __shfl_xor(lrun, 32);
;         inv = 1.0f / lrun;
;         if (c == 0) {
;             int tq_ = threadIdx.x; asm volatile("" : "+v"(tq_)); float* st_ = stash + tq_ * 64;
; #pragma unroll
;             for (int i = 0; i < 4; ++i)
; #pragma unroll
;                 for (int r = 0; r < 16; r += 4) *(GAS f32x4*)(st_ + i * 16 + r) = (f32x4){o[i][r] * inv, o[i][r + 1] * inv, o[i][r + 2] * inv, o[i][r + 3] * inv};
;         }
.Lmy_skip_pf:
	v_add_u32_e32 v72, s25, v220
	ds_read_b128 v[80:83], v72 offset:25376
	ds_read_b128 v[84:87], v72 offset:29984
	ds_read_b128 v[88:91], v72 offset:34592
	ds_read_b128 v[92:95], v72 offset:39200
	ds_read_b128 v[96:99], v72 offset:25408
	ds_read_b128 v[100:103], v72 offset:30016
	ds_read_b128 v[104:107], v72 offset:34624
	ds_read_b128 v[108:111], v72 offset:39232
	ds_read_b128 v[204:207], v72 offset:25440
	ds_read_b128 v[208:211], v72 offset:30048
	ds_read_b128 v[212:215], v72 offset:34656
	ds_read_b128 v[216:219], v72 offset:39264
	v_mfma_f32_32x32x16_bf16 v[0:15], v[196:199], v[200:203], v[0:15]
	v_mfma_f32_32x32x16_bf16 v[48:63], v[192:195], v[200:203], v[48:63]
	v_mfma_f32_32x32x16_bf16 v[32:47], v[188:191], v[200:203], v[32:47]
	v_mfma_f32_32x32x16_bf16 v[16:31], v[184:187], v[200:203], v[16:31]
	s_waitcnt lgkmcnt(8)
	v_mfma_f32_32x32x16_bf16 v[0:15], v[80:83], v[180:183], v[0:15]
	v_mfma_f32_32x32x16_bf16 v[48:63], v[84:87], v[180:183], v[48:63]
	v_mfma_f32_32x32x16_bf16 v[32:47], v[88:91], v[180:183], v[32:47]
	v_mfma_f32_32x32x16_bf16 v[16:31], v[92:95], v[180:183], v[16:31]
	s_waitcnt lgkmcnt(4)
	v_mfma_f32_32x32x16_bf16 v[0:15], v[96:99], v[172:175], v[0:15]
	v_mfma_f32_32x32x16_bf16 v[48:63], v[100:103], v[172:175], v[48:63]
	v_mfma_f32_32x32x16_bf16 v[32:47], v[104:107], v[172:175], v[32:47]
	v_mfma_f32_32x32x16_bf16 v[16:31], v[108:111], v[172:175], v[16:31]
	s_waitcnt lgkmcnt(0)
	s_barrier
	v_mfma_f32_32x32x16_bf16 v[0:15], v[204:207], v[164:167], v[0:15]
	v_mfma_f32_32x32x16_bf16 v[48:63], v[208:211], v[164:167], v[48:63]
	v_mfma_f32_32x32x16_bf16 v[32:47], v[212:215], v[164:167], v[32:47]
	v_mfma_f32_32x32x16_bf16 v[16:31], v[216:219], v[164:167], v[16:31]
	ds_bpermute_b32 v64, v246, v249
	s_waitcnt lgkmcnt(0)
	v_add_f32_e32 v64, v249, v64
	v_div_scale_f32 v65, s[28:29], v64, v64, 1.0
	v_rcp_f32_e32 v66, v65
	s_mov_b64 s[28:29], -1
	v_fma_f32 v67, -v65, v66, 1.0
	v_fmac_f32_e32 v66, v67, v66
	v_div_scale_f32 v67, vcc, 1.0, v64, 1.0
	v_mul_f32_e32 v68, v67, v66
	v_fma_f32 v69, -v65, v68, v67
	v_fmac_f32_e32 v68, v69, v66
	v_fma_f32 v65, -v65, v68, v67
	v_div_fmas_f32 v65, v65, v66, v68
	v_div_fixup_f32 v64, v65, v64, 1.0
	s_and_b64 vcc, exec, s[26:27]
	s_cbranch_vccz .LBB0_333
	v_mov_b32_e32 v65, v254
	s_mov_b64 s[28:29], 0
	v_lshlrev_b32_e32 v70, 4, v65
	v_pk_mul_f32 v[66:67], v[0:1], v[64:65] op_sel_hi:[1,0]
	v_pk_mul_f32 v[68:69], v[2:3], v[64:65] op_sel_hi:[1,0]
	global_store_dwordx4 v70, v[66:69], s[66:67]
	v_pk_mul_f32 v[84:85], v[4:5], v[64:65] op_sel_hi:[1,0]
	v_pk_mul_f32 v[86:87], v[6:7], v[64:65] op_sel_hi:[1,0]
	s_add_u32 s100, s66, 0x2000
	s_addc_u32 s101, s67, 0
	global_store_dwordx4 v70, v[84:87], s[100:101]
	v_pk_mul_f32 v[66:67], v[8:9], v[64:65] op_sel_hi:[1,0]
	v_pk_mul_f32 v[68:69], v[10:11], v[64:65] op_sel_hi:[1,0]
	s_add_u32 s100, s66, 0x4000
	s_addc_u32 s101, s67, 0
	global_store_dwordx4 v70, v[66:69], s[100:101]
	v_pk_mul_f32 v[84:85], v[12:13], v[64:65] op_sel_hi:[1,0]
	v_pk_mul_f32 v[86:87], v[14:15], v[64:65] op_sel_hi:[1,0]
	s_add_u32 s100, s66, 0x6000
	s_addc_u32 s101, s67, 0
	global_store_dwordx4 v70, v[84:87], s[100:101]
	v_pk_mul_f32 v[66:67], v[48:49], v[64:65] op_sel_hi:[1,0]
	v_pk_mul_f32 v[68:69], v[50:51], v[64:65] op_sel_hi:[1,0]
	s_add_u32 s100, s66, 0x8000
	s_addc_u32 s101, s67, 0
	global_store_dwordx4 v70, v[66:69], s[100:101]
	v_pk_mul_f32 v[84:85], v[52:53], v[64:65] op_sel_hi:[1,0]
	v_pk_mul_f32 v[86:87], v[54:55], v[64:65] op_sel_hi:[1,0]
	s_add_u32 s100, s66, 0xa000
	s_addc_u32 s101, s67, 0
	global_store_dwordx4 v70, v[84:87], s[100:101]
	v_pk_mul_f32 v[66:67], v[56:57], v[64:65] op_sel_hi:[1,0]
	v_pk_mul_f32 v[68:69], v[58:59], v[64:65] op_sel_hi:[1,0]
	s_add_u32 s100, s66, 0xc000
	s_addc_u32 s101, s67, 0
	global_store_dwordx4 v70, v[66:69], s[100:101]
	v_pk_mul_f32 v[84:85], v[60:61], v[64:65] op_sel_hi:[1,0]
	v_pk_mul_f32 v[86:87], v[62:63], v[64:65] op_sel_hi:[1,0]
	s_add_u32 s100, s66, 0xe000
	s_addc_u32 s101, s67, 0
	global_store_dwordx4 v70, v[84:87], s[100:101]
	v_pk_mul_f32 v[66:67], v[32:33], v[64:65] op_sel_hi:[1,0]
	v_pk_mul_f32 v[68:69], v[34:35], v[64:65] op_sel_hi:[1,0]
	s_add_u32 s100, s66, 0x10000
	s_addc_u32 s101, s67, 0
	global_store_dwordx4 v70, v[66:69], s[100:101]
	v_pk_mul_f32 v[84:85], v[36:37], v[64:65] op_sel_hi:[1,0]
	v_pk_mul_f32 v[86:87], v[38:39], v[64:65] op_sel_hi:[1,0]
	s_add_u32 s100, s66, 0x12000
	s_addc_u32 s101, s67, 0
	global_store_dwordx4 v70, v[84:87], s[100:101]
	v_pk_mul_f32 v[66:67], v[40:41], v[64:65] op_sel_hi:[1,0]
	v_pk_mul_f32 v[68:69], v[42:43], v[64:65] op_sel_hi:[1,0]
	s_add_u32 s100, s66, 0x14000
	s_addc_u32 s101, s67, 0
	global_store_dwordx4 v70, v[66:69], s[100:101]
	v_pk_mul_f32 v[84:85], v[44:45], v[64:65] op_sel_hi:[1,0]
	v_pk_mul_f32 v[86:87], v[46:47], v[64:65] op_sel_hi:[1,0]
	s_add_u32 s100, s66, 0x16000
	s_addc_u32 s101, s67, 0
	global_store_dwordx4 v70, v[84:87], s[100:101]
	v_pk_mul_f32 v[66:67], v[16:17], v[64:65] op_sel_hi:[1,0]
	v_pk_mul_f32 v[68:69], v[18:19], v[64:65] op_sel_hi:[1,0]
	s_add_u32 s100, s66, 0x18000
	s_addc_u32 s101, s67, 0
	global_store_dwordx4 v70, v[66:69], s[100:101]
	v_pk_mul_f32 v[84:85], v[20:21], v[64:65] op_sel_hi:[1,0]
	v_pk_mul_f32 v[86:87], v[22:23], v[64:65] op_sel_hi:[1,0]
	s_add_u32 s100, s66, 0x1a000
	s_addc_u32 s101, s67, 0
	global_store_dwordx4 v70, v[84:87], s[100:101]
	v_pk_mul_f32 v[66:67], v[24:25], v[64:65] op_sel_hi:[1,0]
	v_pk_mul_f32 v[68:69], v[26:27], v[64:65] op_sel_hi:[1,0]
	s_add_u32 s100, s66, 0x1c000
	s_addc_u32 s101, s67, 0
	global_store_dwordx4 v70, v[66:69], s[100:101]
	v_pk_mul_f32 v[84:85], v[28:29], v[64:65] op_sel_hi:[1,0]
	v_pk_mul_f32 v[86:87], v[30:31], v[64:65] op_sel_hi:[1,0]
	s_add_u32 s100, s66, 0x1e000
	s_addc_u32 s101, s67, 0
	global_store_dwordx4 v70, v[84:87], s[100:101]
	s_branch .LBB0_333
